# v9 + NSA item->tile remap (wave w of block row r takes tile 32w+r: light..heavy mix per CU), uniform sparse dealing table
# speedup vs baseline: 1.0110x; 1.0110x over previous
; template <class T> DI T* opqp(T* p) { unsigned long long v = (unsigned long long)p; asm volatile("" : "+s"(v)); return (T*)v; }
; DI int tid_of(int wave_s) { unsigned z = 0; asm volatile("" : "+s"(z)); int l = __builtin_amdgcn_mbcnt_hi(~0u, __builtin_amdgcn_mbcnt_lo(~0u, z)); return wave_s * 64 + l; }
; DI int pi_row(int r) { return (r & 0x13) | ((r & 4) << 1) | ((r & 8) >> 1); }
; #define P kparams()
; DI void nsa_phase(unsigned char* lds, KParamPtr P, int wv) {
;   unsigned char* wsq = opqp(P->ws);
;   const float* tab = (const float*)(lds + LDS_TAB);
;   const int tid = tid_of(wv), lane = tid & 63, wave = tid >> 6, l31 = lane & 31, hh = lane >> 5;
;   unsigned char* selL = lds + LDS_WORK + wave * 512;
;   float* scw = (float*)(lds + LDS_WORK + 4096 + wave * 16384);
;   const bf16_t* proj = (const bf16_t*)(wsq + OFF_U + U_PROJ);
;   const bf16_t* vsT = (const bf16_t*)(wsq + OFF_U + U_VST);
;   const bf16_t* vwT = (const bf16_t*)(wsq + OFF_U + U_VWT);
;   const bf16_t* kc = (const bf16_t*)(wsq + OFF_MISC + MS_KC);
;   const bf16_t* vcT = (const bf16_t*)(wsq + OFF_MISC + MS_VCT);
;   float* part = (float*)(wsq + OFF_HB);
;   bf16_t* ao = (bf16_t*)(wsq + OFF_AO);
;   const int nw = gridDim.x * 8, gw = blockIdx.x * 8 + wave;
;   const int pr = pi_row(l31);
;   for (int it = gw; it < 2048; it += nw) {
;     const int blk_ = it >> 3, combo_ = blk_ & 7;
;     const int b = combo_ >> 1, g = combo_ & 1, tile = ((blk_ >> 3) << 3) + (it & 7), t0 = tile * 32, t = t0 + l31;
;     const size_t tok = (size_t)b * SEQ + t;
.LBB0_933:
	s_or_b64 exec, exec, s[4:5]
	s_mov_b64 s[4:5], s[64:65]
	s_barrier
	s_load_dwordx2 s[6:7], s[4:5], 0xc8
	s_mov_b32 s2, s89
	s_waitcnt lgkmcnt(0)
	v_readlane_b32 s4, v254, 0
	v_mbcnt_lo_u32_b32 v0, -1, s2
	v_mbcnt_hi_u32_b32 v4, -1, v0
	v_add_u32_e32 v3, s4, v4
	v_ashrrev_i32_e32 v2, 6, v3
	v_readlane_b32 s2, v254, 33
	v_readlane_b32 s5, v254, 1
	s_nop 0
	v_add_u32_e32 v165, s2, v2
	s_movk_i32 s2, 0x800
	v_cmp_gt_i32_e32 vcc, s2, v165
	s_and_saveexec_b64 s[18:19], vcc
	s_cbranch_execz .LBB0_1158
	v_lshlrev_b32_e32 v6, 1, v4
	v_lshrrev_b32_e32 v8, 1, v4
	v_lshl_add_u32 v164, v2, 9, 0
	v_and_b32_e32 v0, 19, v4
	v_and_b32_e32 v6, 8, v6
	v_and_b32_e32 v7, 4, v8
	s_movk_i32 s2, 0x3e00
	v_and_b32_e32 v5, 63, v4
	s_add_u32 s20, s6, 0x8000000
	v_or3_b32 v224, v7, v0, v6
	v_mad_u64_u32 v[6:7], s[4:5], v2, s2, v[164:165]
	v_and_b32_e32 v222, 31, v4
	v_bfe_u32 v223, v4, 5, 1
	s_addc_u32 s21, s7, 0
	v_lshlrev_b32_e32 v7, 2, v5
	v_cmp_gt_u32_e64 s[4:5], 32, v5
	v_and_b32_e32 v11, 15, v4
	v_bfe_u32 v229, v4, 2, 2
	v_and_b32_e32 v230, 3, v4
	v_and_b32_e32 v170, 24, v8
	v_mov_b32_e32 v171, v1
	v_and_b32_e32 v4, 48, v4
	v_mov_b32_e32 v5, v1
	v_lshlrev_b32_e32 v0, 4, v223
	v_lshl_add_u64 v[172:173], s[20:21], 0, v[4:5]
	v_lshl_add_u64 v[174:175], s[6:7], 0, v[4:5]
	v_lshl_add_u64 v[4:5], s[6:7], 0, v[170:171]
	s_mov_b64 s[8:9], 0x4000000
	v_lshl_add_u64 v[176:177], v[4:5], 0, s[8:9]
	v_lshl_or_b32 v4, v224, 7, v0
	v_mov_b32_e32 v5, v1
	s_add_u32 s22, s6, 0x11e00000
	v_lshl_add_u64 v[166:167], s[20:21], 0, v[0:1]
	v_lshlrev_b32_e32 v10, 2, v222
	v_lshl_add_u64 v[168:169], s[6:7], 0, v[0:1]
	v_lshl_add_u64 v[4:5], s[6:7], 0, v[4:5]
	s_mov_b64 s[8:9], 0x1a600000
	v_lshl_or_b32 v0, v222, 10, v0
	s_addc_u32 s23, s7, 0
	v_add_u32_e32 v225, v6, v7
	v_add_u32_e32 v226, v6, v10
	v_lshlrev_b32_e32 v6, 8, v223
	v_bfe_u32 v171, v3, 6, 3
	v_lshl_add_u64 v[178:179], v[4:5], 0, s[8:9]
	v_lshlrev_b32_e32 v3, 7, v223
	v_lshl_add_u64 v[4:5], s[6:7], 0, v[0:1]
	v_lshlrev_b32_e32 v0, 14, v2
	v_lshlrev_b32_e32 v9, 3, v223
	v_xor_b32_e32 v227, 0x80, v7
	v_lshlrev_b32_e32 v7, 4, v222
	v_sub_u32_e32 v234, v222, v3
	v_lshlrev_b32_e32 v3, 10, v171
	s_mov_b64 s[8:9], 0x1a708020
	v_or3_b32 v0, v0, v6, v10
	v_readlane_b32 s2, v255, 9
	s_add_u32 s24, s6, 0x12680020
	v_lshlrev_b32_e32 v228, 1, v223
	v_or_b32_e32 v232, 0x400, v9
	v_or_b32_e32 v233, 0x300, v170
	v_add_u32_e32 v235, 0xfffffdf1, v3
	v_lshl_add_u64 v[180:181], v[4:5], 0, s[8:9]
	v_add_u32_e32 v236, s2, v0
	v_or_b32_e32 v237, 31, v3
	v_sub_u32_e32 v238, v222, v9
	s_addc_u32 s25, s7, 0
	v_lshl_or_b32 v239, v222, 13, v9
	s_mov_b64 s[26:27], 0
	v_add_u32_e32 v240, v164, v7
	v_lshlrev_b32_e32 v241, 13, v11
	s_branch .LBB0_936

; DI void nsa_phase(unsigned char* lds, KParamPtr P, int wv) {
;     ...
;   for (int it = gw; it < 2048; it += nw) {
;     const int blk_ = it >> 3, combo_ = blk_ & 7;
;     const int b = combo_ >> 1, g = combo_ & 1, tile = ((blk_ >> 3) << 3) + (it & 7), t0 = tile * 32, t = t0 + l31;
;     const size_t tok = (size_t)b * SEQ + t;
;     const bf16_t* kcb = kc + (size_t)((b * 2 + g) * 512) * 64;
;     const bf16_t* vcb = vcT + (size_t)((b * 2 + g) * 64) * 512;
; #pragma unroll 1
;     for (int x = 0; x < 64; ++x) scw[x * 64 + lane] = 0.f;
;     const int nkt = (2 * tile + 1 + 31) >> 5;
.LBB0_937:
	v_lshl_add_u32 v0, s6, 8, v225
	v_lshl_add_u32 v2, s2, 8, v225
	s_add_i32 s6, s6, 2
	s_add_i32 s2, s2, 2
	s_add_i32 s7, s7, -2
	s_cmp_lg_u32 s7, 0
	ds_write_b32 v0, v1 offset:12288
	ds_write_b32 v2, v1 offset:12288
	s_cbranch_scc1 .LBB0_937
	v_ashrrev_i32_e32 v6, 3, v165
	v_lshrrev_b32_e32 v244, 3, v6
	v_lshl_add_u32 v244, v171, 5, v244
	v_lshlrev_b32_e32 v242, 5, v244
	v_lshlrev_b32_e32 v0, 12, v6
	v_or_b32_e32 v2, v242, v222
	v_and_b32_e32 v182, 0x6000, v0
	v_ashrrev_i32_e32 v3, 31, v2
	v_mov_b32_e32 v183, v1
	v_lshl_add_u64 v[2:3], v[2:3], 0, v[182:183]
	v_mov_b64_e32 v[4:5], s[20:21]
	v_mad_u64_u32 v[184:185], s[6:7], v2, s87, v[166:167]
	v_mad_u64_u32 v[186:187], s[8:9], v2, s87, v[4:5]
	v_mad_i32_i24 v185, v3, s87, v185
	v_mad_i32_i24 v187, v3, s87, v187
	v_lshlrev_b64 v[2:3], 11, v[2:3]
	v_and_b32_e32 v163, 7, v6
	v_lshl_add_u32 v0, v244, 1, 32
	v_lshl_add_u64 v[188:189], v[168:169], 0, v[2:3]
	v_lshlrev_b32_e32 v2, 2, v6
	v_and_b32_e32 v245, 1, v6
	v_ashrrev_i32_e32 v247, 5, v0
	v_lshlrev_b32_e32 v0, 16, v163
	v_and_b32_e32 v246, 0xffffffe0, v2
	v_lshlrev_b32_e32 v243, 2, v245
	v_lshl_add_u64 v[190:191], v[178:179], 0, v[0:1]
	s_mov_b32 s16, 0
	v_cmp_lt_i32_e64 s[6:7], 0, v247
	v_add_u32_e32 v248, v235, v246
	v_lshl_add_u64 v[192:193], v[180:181], 0, v[0:1]
	s_branch .LBB0_941

; DI void dsa_sparse_phase(unsigned char* lds, KParamPtr P, int wv) {
;     ...
;   const bool dealt = (gridDim.x == 256);
;   const int g_lo = dealt ? (int)kSpStart[blockIdx.x >> 3] : 0, g_n = dealt ? (int)kSpStart[(blockIdx.x >> 3) + 1] - g_lo : 0;
_ZL8kSpStart:
	.short	0
	.short	16
	.short	32
	.short	48
	.short	64
	.short	80
	.short	96
	.short	112
	.short	128
	.short	144
	.short	160
	.short	176
	.short	192
	.short	208
	.short	224
	.short	240
	.short	256
	.short	272
	.short	288
	.short	304
	.short	320
	.short	336
	.short	352
	.short	368
	.short	384
	.short	400
	.short	416
	.short	432
	.short	448
	.short	464
	.short	480
	.short	496
	.short	512
	.size	_ZL8kSpStart, 66

; __global__ void __launch_bounds__(NTHREADS) mega(Params P0) {
	.type	__hip_cuid_1ffeae86b4d56f0d,@object
